# attention epilogue via wave-private LDS transpose: 8 full-row dwordx4 stores per wave (second measurement, candidate)
# baseline (speedup 1.0000x reference)
.LBB0_1166:
	v_readlane_b32 s12, v243, 21
	v_readlane_b32 s13, v243, 22
	v_readlane_b32 s16, v243, 25
	v_readlane_b32 s17, v243, 26
	v_readlane_b32 s20, v243, 29
	v_readlane_b32 s21, v243, 30
	v_ashrrev_i32_e32 v165, 31, v164
	s_mov_b64 s[12:13], s[16:17]
	s_mov_b64 s[16:17], s[20:21]
	v_lshl_add_u64 v[80:81], v[164:165], 2, s[16:17]
	v_mov_b32_e32 v80, v240
	ds_bpermute_b32 v82, v202, v188
	v_readlane_b32 s11, v243, 60
	v_readlane_b32 s6, v243, 50
	v_readlane_b32 s7, v243, 51
	v_readlane_b32 s14, v243, 23
	s_waitcnt lgkmcnt(0)
	v_add_f32_e32 v82, v188, v82
	v_readlane_b32 s15, v243, 24
	v_readlane_b32 s18, v243, 27
	v_readlane_b32 s19, v243, 28
	v_readlane_b32 s22, v243, 31
	v_readlane_b32 s23, v243, 32
	v_readlane_b32 s24, v243, 33
	v_readlane_b32 s25, v243, 34
	v_readlane_b32 s26, v243, 35
	v_readlane_b32 s27, v243, 36
	s_waitcnt vmcnt(0)
	v_fmamk_f32 v80, v80, 0x3fb8aa3b, v0
	v_exp_f32_e32 v83, v80
	v_lshl_add_u64 v[80:81], v[162:163], 1, v[154:155]
	v_add_f32_e32 v82, v83, v82
	v_div_scale_f32 v84, s[0:1], v82, v82, 1.0
	v_rcp_f32_e32 v85, v84
	s_nop 0
	v_fma_f32 v86, -v84, v85, 1.0
	v_fmac_f32_e32 v85, v86, v85
	v_div_scale_f32 v86, vcc, 1.0, v82, 1.0
	v_mul_f32_e32 v87, v86, v85
	v_fma_f32 v88, -v84, v87, v86
	v_fmac_f32_e32 v87, v88, v85
	v_fma_f32 v84, -v84, v87, v86
	v_div_fmas_f32 v84, v84, v85, v87
	v_div_fixup_f32 v82, v84, v82, 1.0
	v_lshlrev_b64 v[84:85], 11, v[160:161]
	v_lshl_add_u64 v[84:85], v[80:81], 0, v[84:85]
	v_and_b32_e32 v252, 63, v168
	v_and_b32_e32 v253, 31, v252
	v_lshrrev_b32_e32 v254, 5, v252
	v_lshrrev_b32_e32 v255, 3, v252
	v_sub_u32_e32 v244, v255, v253
	v_lshlrev_b32_e32 v244, 11, v244
	v_and_b32_e32 v245, 7, v252
	v_lshl_add_u32 v244, v245, 4, v244
	v_lshlrev_b32_e32 v246, 3, v254
	v_sub_u32_e32 v244, v244, v246
	v_lshrrev_b32_e32 v246, 6, v168
	v_mul_u32_u24_e32 v246, 0x1200, v246
	v_add_u32_e32 v246, 0x11800, v246
	v_mul_u32_u24_e32 v247, 0x90, v253
	v_add_u32_e32 v247, v247, v246
	v_lshl_add_u32 v254, v254, 4, v247
	v_mul_u32_u24_e32 v247, 0x90, v255
	v_add_u32_e32 v247, v247, v246
	v_lshl_add_u32 v255, v245, 4, v247
	v_mov_b32_e32 v252, v244
	v_ashrrev_i32_e32 v253, 31, v252
	s_mov_b32 s98, 0x4000
	s_mov_b32 s99, 0
	v_pk_mul_f32 v[48:49], v[48:49], v[82:83] op_sel_hi:[1,0]
	v_pk_mul_f32 v[50:51], v[50:51], v[82:83] op_sel_hi:[1,0]
	v_pk_mul_f32 v[52:53], v[52:53], v[82:83] op_sel_hi:[1,0]
	v_pk_mul_f32 v[54:55], v[54:55], v[82:83] op_sel_hi:[1,0]
	v_cvt_pk_bf16_f32 v244, v48, v49
	v_cvt_pk_bf16_f32 v245, v50, v51
	v_cvt_pk_bf16_f32 v246, v52, v53
	v_cvt_pk_bf16_f32 v247, v54, v55
	s_nop 1
	v_permlane32_swap_b32_e32 v244, v246
	v_permlane32_swap_b32_e32 v245, v247
	ds_write_b128 v254, v[244:247] offset:64
	v_pk_mul_f32 v[56:57], v[56:57], v[82:83] op_sel_hi:[1,0]
	v_pk_mul_f32 v[58:59], v[58:59], v[82:83] op_sel_hi:[1,0]
	v_pk_mul_f32 v[60:61], v[60:61], v[82:83] op_sel_hi:[1,0]
	v_pk_mul_f32 v[62:63], v[62:63], v[82:83] op_sel_hi:[1,0]
	v_cvt_pk_bf16_f32 v248, v56, v57
	v_cvt_pk_bf16_f32 v249, v58, v59
	v_cvt_pk_bf16_f32 v250, v60, v61
	v_cvt_pk_bf16_f32 v251, v62, v63
	s_nop 1
	v_permlane32_swap_b32_e32 v248, v250
	v_permlane32_swap_b32_e32 v249, v251
	ds_write_b128 v254, v[248:251] offset:96
	ds_bpermute_b32 v48, v202, v187
	v_pk_mul_f32 v[64:65], v[64:65], v[82:83] op_sel_hi:[1,0]
	v_pk_mul_f32 v[66:67], v[66:67], v[82:83] op_sel_hi:[1,0]
	v_pk_mul_f32 v[68:69], v[68:69], v[82:83] op_sel_hi:[1,0]
	v_pk_mul_f32 v[70:71], v[70:71], v[82:83] op_sel_hi:[1,0]
	v_cvt_pk_bf16_f32 v244, v64, v65
	v_cvt_pk_bf16_f32 v245, v66, v67
	v_cvt_pk_bf16_f32 v246, v68, v69
	v_cvt_pk_bf16_f32 v247, v70, v71
	s_nop 1
	v_permlane32_swap_b32_e32 v244, v246
	v_permlane32_swap_b32_e32 v245, v247
	ds_write_b128 v254, v[244:247]
	v_pk_mul_f32 v[72:73], v[72:73], v[82:83] op_sel_hi:[1,0]
	v_pk_mul_f32 v[74:75], v[74:75], v[82:83] op_sel_hi:[1,0]
	v_pk_mul_f32 v[76:77], v[76:77], v[82:83] op_sel_hi:[1,0]
	v_pk_mul_f32 v[78:79], v[78:79], v[82:83] op_sel_hi:[1,0]
	v_cvt_pk_bf16_f32 v248, v72, v73
	v_cvt_pk_bf16_f32 v249, v74, v75
	v_cvt_pk_bf16_f32 v250, v76, v77
	v_cvt_pk_bf16_f32 v251, v78, v79
	s_nop 1
	v_permlane32_swap_b32_e32 v248, v250
	v_permlane32_swap_b32_e32 v249, v251
	ds_write_b128 v254, v[248:251] offset:32
	s_waitcnt lgkmcnt(0)
	v_add_f32_e32 v48, v187, v48
	v_add_f32_e32 v48, v83, v48
	v_lshl_add_u64 v[84:85], v[84:85], 0, v[252:253]
	ds_read_b128 v[244:247], v255
	ds_read_b128 v[248:251], v255 offset:1152
	s_waitcnt lgkmcnt(1)
	global_store_dwordx4 v[84:85], v[244:247], off
	v_lshl_add_u64 v[84:85], v[84:85], 0, s[98:99]
	s_waitcnt lgkmcnt(0)
	global_store_dwordx4 v[84:85], v[248:251], off
	v_lshl_add_u64 v[84:85], v[84:85], 0, s[98:99]
	ds_read_b128 v[244:247], v255 offset:2304
	ds_read_b128 v[248:251], v255 offset:3456
	s_waitcnt lgkmcnt(1)
	global_store_dwordx4 v[84:85], v[244:247], off
	v_lshl_add_u64 v[84:85], v[84:85], 0, s[98:99]
	s_waitcnt lgkmcnt(0)
	global_store_dwordx4 v[84:85], v[248:251], off
	v_div_scale_f32 v49, s[0:1], v48, v48, 1.0
	v_rcp_f32_e32 v50, v49
	s_nop 0
	v_fma_f32 v51, -v49, v50, 1.0
	v_fmac_f32_e32 v50, v51, v50
	v_div_scale_f32 v51, vcc, 1.0, v48, 1.0
	v_mul_f32_e32 v52, v51, v50
	v_fma_f32 v53, -v49, v52, v51
	v_fmac_f32_e32 v52, v53, v50
	v_fma_f32 v49, -v49, v52, v51
	v_div_fmas_f32 v49, v49, v50, v52
	v_div_fixup_f32 v48, v49, v48, 1.0
	v_lshlrev_b64 v[50:51], 11, v[166:167]
	v_lshl_add_u64 v[50:51], v[80:81], 0, v[50:51]
	v_pk_mul_f32 v[32:33], v[32:33], v[48:49] op_sel_hi:[1,0]
	v_pk_mul_f32 v[34:35], v[34:35], v[48:49] op_sel_hi:[1,0]
	v_pk_mul_f32 v[36:37], v[36:37], v[48:49] op_sel_hi:[1,0]
	v_pk_mul_f32 v[38:39], v[38:39], v[48:49] op_sel_hi:[1,0]
	v_cvt_pk_bf16_f32 v244, v32, v33
	v_cvt_pk_bf16_f32 v245, v34, v35
	v_cvt_pk_bf16_f32 v246, v36, v37
	v_cvt_pk_bf16_f32 v247, v38, v39
	s_nop 1
	v_permlane32_swap_b32_e32 v244, v246
	v_permlane32_swap_b32_e32 v245, v247
	ds_write_b128 v254, v[244:247]
	v_pk_mul_f32 v[40:41], v[40:41], v[48:49] op_sel_hi:[1,0]
	v_pk_mul_f32 v[42:43], v[42:43], v[48:49] op_sel_hi:[1,0]
	v_pk_mul_f32 v[44:45], v[44:45], v[48:49] op_sel_hi:[1,0]
	v_pk_mul_f32 v[46:47], v[46:47], v[48:49] op_sel_hi:[1,0]
	v_cvt_pk_bf16_f32 v248, v40, v41
	v_cvt_pk_bf16_f32 v249, v42, v43
	v_cvt_pk_bf16_f32 v250, v44, v45
	v_cvt_pk_bf16_f32 v251, v46, v47
	s_nop 1
	v_permlane32_swap_b32_e32 v248, v250
	v_permlane32_swap_b32_e32 v249, v251
	ds_write_b128 v254, v[248:251] offset:32
	v_pk_mul_f32 v[16:17], v[16:17], v[48:49] op_sel_hi:[1,0]
	v_pk_mul_f32 v[18:19], v[18:19], v[48:49] op_sel_hi:[1,0]
	v_pk_mul_f32 v[20:21], v[20:21], v[48:49] op_sel_hi:[1,0]
	v_pk_mul_f32 v[22:23], v[22:23], v[48:49] op_sel_hi:[1,0]
	v_cvt_pk_bf16_f32 v244, v16, v17
	v_cvt_pk_bf16_f32 v245, v18, v19
	v_cvt_pk_bf16_f32 v246, v20, v21
	v_cvt_pk_bf16_f32 v247, v22, v23
	s_nop 1
	v_permlane32_swap_b32_e32 v244, v246
	v_permlane32_swap_b32_e32 v245, v247
	ds_write_b128 v254, v[244:247] offset:64
	v_pk_mul_f32 v[24:25], v[24:25], v[48:49] op_sel_hi:[1,0]
	v_pk_mul_f32 v[26:27], v[26:27], v[48:49] op_sel_hi:[1,0]
	v_pk_mul_f32 v[28:29], v[28:29], v[48:49] op_sel_hi:[1,0]
	v_pk_mul_f32 v[30:31], v[30:31], v[48:49] op_sel_hi:[1,0]
	v_cvt_pk_bf16_f32 v248, v24, v25
	v_cvt_pk_bf16_f32 v249, v26, v27
	v_cvt_pk_bf16_f32 v250, v28, v29
	v_cvt_pk_bf16_f32 v251, v30, v31
	s_nop 1
	v_permlane32_swap_b32_e32 v248, v250
	v_permlane32_swap_b32_e32 v249, v251
	ds_write_b128 v254, v[248:251] offset:96
	v_lshl_add_u64 v[50:51], v[50:51], 0, v[252:253]
	s_waitcnt lgkmcnt(0)
	ds_read_b128 v[244:247], v255
	ds_read_b128 v[248:251], v255 offset:1152
	s_waitcnt lgkmcnt(1)
	global_store_dwordx4 v[50:51], v[244:247], off
	v_lshl_add_u64 v[50:51], v[50:51], 0, s[98:99]
	s_waitcnt lgkmcnt(0)
	global_store_dwordx4 v[50:51], v[248:251], off
	v_lshl_add_u64 v[50:51], v[50:51], 0, s[98:99]
	ds_read_b128 v[244:247], v255 offset:2304
	ds_read_b128 v[248:251], v255 offset:3456
	s_waitcnt lgkmcnt(1)
	global_store_dwordx4 v[50:51], v[244:247], off
	v_lshl_add_u64 v[50:51], v[50:51], 0, s[98:99]
	s_waitcnt lgkmcnt(0)
	global_store_dwordx4 v[50:51], v[248:251], off
	v_readlane_b32 s0, v243, 1
	v_readlane_b32 s2, v243, 3
	s_nop 3
	s_add_i32 s11, s11, s2
	s_cmpk_gt_i32 s11, 0x7ff
	v_readlane_b32 s1, v243, 2
	v_readlane_b32 s3, v243, 4
	s_cbranch_scc1 .LBB0_1202
